# decode-row small GEMMs (P4,P5,P7): all K-fragment loads issued up front into own registers, one wait, then the MFMA chain
# baseline (speedup 1.0000x reference)
.LBB0_593:
	v_and_or_b32 v14, s6, -16, v1
	v_ashrrev_i32_e32 v15, 31, v14
	v_lshlrev_b64 v[14:15], 11, v[14:15]
	v_lshl_add_u64 v[50:51], v[6:7], 0, v[14:15]
	global_load_dwordx4 v[14:17], v[50:51], off
	s_and_b32 s12, s8, 0x60
	v_or_b32_e32 v12, s12, v11
	v_lshlrev_b32_e32 v2, 11, v12
	v_lshl_add_u64 v[52:53], v[4:5], 0, v[2:3]
	global_load_dwordx4 v[18:21], v[50:51], off offset:64
	global_load_dwordx4 v[22:25], v[52:53], off
	global_load_dwordx4 v[26:29], v[52:53], off offset:64
	global_load_dwordx4 v[30:33], v[50:51], off offset:128
	global_load_dwordx4 v[34:37], v[52:53], off offset:128
	global_load_dwordx4 v[38:41], v[50:51], off offset:192
	global_load_dwordx4 v[42:45], v[52:53], off offset:192
	s_and_b64 vcc, exec, s[0:1]
	global_load_dwordx4 v[54:57], v[50:51], off offset:256
	global_load_dwordx4 v[58:61], v[52:53], off offset:256
	global_load_dwordx4 v[62:65], v[50:51], off offset:320
	global_load_dwordx4 v[66:69], v[52:53], off offset:320
	global_load_dwordx4 v[70:73], v[50:51], off offset:384
	global_load_dwordx4 v[74:77], v[52:53], off offset:384
	global_load_dwordx4 v[78:81], v[50:51], off offset:448
	global_load_dwordx4 v[82:85], v[52:53], off offset:448
	s_waitcnt vmcnt(0)
	v_mfma_f32_16x16x32_bf16 v[14:17], v[14:17], v[22:25], 0
	v_mfma_f32_16x16x32_bf16 v[14:17], v[18:21], v[26:29], v[14:17]
	v_mfma_f32_16x16x32_bf16 v[14:17], v[30:33], v[34:37], v[14:17]
	v_mfma_f32_16x16x32_bf16 v[14:17], v[38:41], v[42:45], v[14:17]
	v_mfma_f32_16x16x32_bf16 v[14:17], v[54:57], v[58:61], v[14:17]
	v_mfma_f32_16x16x32_bf16 v[14:17], v[62:65], v[66:69], v[14:17]
	v_mfma_f32_16x16x32_bf16 v[14:17], v[70:73], v[74:77], v[14:17]
	v_mfma_f32_16x16x32_bf16 v[14:17], v[78:81], v[82:85], v[14:17]
	s_nop 7
	ds_write_b128 v9, v[14:17]
	s_waitcnt lgkmcnt(0)
	s_barrier
	s_cbranch_vccnz .LBB0_592
	s_and_b32 s12, s11, 0x3ffffffc
	v_or_b32_e32 v34, 0x4000, v12
	v_mov_b64_e32 v[12:13], s[92:93]
	v_or_b32_e32 v32, s12, v8
	v_mad_u64_u32 v[12:13], s[12:13], v34, s10, v[12:13]
	s_and_b32 s12, s4, 0xffffff00
	s_ashr_i32 s13, s12, 31
	v_lshlrev_b32_e32 v2, 3, v32
	v_lshl_add_u64 v[12:13], s[12:13], 1, v[12:13]
	v_and_b32_e32 v2, 0xf8, v2
	v_lshl_add_u64 v[12:13], v[12:13], 0, v[2:3]
	global_load_dwordx2 v[28:29], v[12:13], off offset:2816
	global_load_dwordx2 v[30:31], v[12:13], off offset:2560
	ds_read_b128 v[12:15], v10
	ds_read_b128 v[16:19], v10 offset:2048
	ds_read_b128 v[20:23], v10 offset:4096
	ds_read_b128 v[24:27], v10 offset:6144
	v_lshlrev_b32_e32 v2, 11, v34
	v_lshlrev_b32_e32 v32, 2, v32
	s_waitcnt lgkmcnt(2)
	v_pk_add_f32 v[14:15], v[14:15], v[18:19]
	v_pk_add_f32 v[12:13], v[12:13], v[16:17]
	s_waitcnt lgkmcnt(0)
	v_pk_add_f32 v[16:17], v[22:23], v[26:27]
	v_pk_add_f32 v[18:19], v[20:21], v[24:25]
	v_lshl_add_u64 v[20:21], s[78:79], 0, v[2:3]
	v_ashrrev_i32_e32 v33, 31, v32
	s_waitcnt vmcnt(1)
	v_lshlrev_b32_e32 v2, 16, v28
	v_and_b32_e32 v23, 0xffff0000, v28
	s_waitcnt vmcnt(0)
	v_and_b32_e32 v24, 0xffff0000, v30
	v_lshlrev_b32_e32 v26, 16, v31
	v_and_b32_e32 v28, 0xffff0000, v31
	v_lshlrev_b32_e32 v22, 16, v30
	v_lshlrev_b32_e32 v25, 16, v29
	v_and_b32_e32 v27, 0xffff0000, v29
	v_fmac_f32_e32 v19, v13, v24
	v_fma_f32 v13, v14, v26, v16
	v_fmac_f32_e32 v17, v15, v28
	v_fma_f32 v12, v12, v22, v18
	v_mul_f32_e32 v13, v13, v25
	v_mul_f32_e32 v14, v17, v27
	v_mul_f32_e32 v2, v12, v2
	v_mul_f32_e32 v12, v19, v23
	v_cvt_pk_bf16_f32 v13, v13, v14
	v_lshl_add_u64 v[14:15], v[32:33], 1, v[20:21]
	v_cvt_pk_bf16_f32 v12, v2, v12
	global_store_dwordx2 v[14:15], v[12:13], off
	s_branch .LBB0_592

.LBB0_764:
	v_and_or_b32 v18, s10, -16, v1
	v_ashrrev_i32_e32 v19, 31, v18
	v_lshlrev_b64 v[18:19], 11, v[18:19]
	v_lshl_add_u64 v[54:55], v[6:7], 0, v[18:19]
	global_load_dwordx4 v[18:21], v[54:55], off
	s_and_b32 s8, s12, 0x60
	v_or_b32_e32 v16, s8, v11
	v_lshlrev_b32_e32 v2, 11, v16
	v_lshl_add_u64 v[56:57], v[4:5], 0, v[2:3]
	global_load_dwordx4 v[22:25], v[54:55], off offset:64
	global_load_dwordx4 v[26:29], v[56:57], off
	global_load_dwordx4 v[30:33], v[56:57], off offset:64
	global_load_dwordx4 v[34:37], v[54:55], off offset:128
	global_load_dwordx4 v[38:41], v[56:57], off offset:128
	global_load_dwordx4 v[42:45], v[54:55], off offset:192
	global_load_dwordx4 v[46:49], v[56:57], off offset:192
	s_and_b64 vcc, exec, s[4:5]
	global_load_dwordx4 v[58:61], v[54:55], off offset:256
	global_load_dwordx4 v[62:65], v[56:57], off offset:256
	global_load_dwordx4 v[66:69], v[54:55], off offset:320
	global_load_dwordx4 v[70:73], v[56:57], off offset:320
	global_load_dwordx4 v[74:77], v[54:55], off offset:384
	global_load_dwordx4 v[78:81], v[56:57], off offset:384
	global_load_dwordx4 v[82:85], v[54:55], off offset:448
	global_load_dwordx4 v[86:89], v[56:57], off offset:448
	s_waitcnt vmcnt(0)
	v_mfma_f32_16x16x32_bf16 v[18:21], v[18:21], v[26:29], 0
	v_mfma_f32_16x16x32_bf16 v[18:21], v[22:25], v[30:33], v[18:21]
	v_mfma_f32_16x16x32_bf16 v[18:21], v[34:37], v[38:41], v[18:21]
	v_mfma_f32_16x16x32_bf16 v[18:21], v[42:45], v[46:49], v[18:21]
	v_mfma_f32_16x16x32_bf16 v[18:21], v[58:61], v[62:65], v[18:21]
	v_mfma_f32_16x16x32_bf16 v[18:21], v[66:69], v[70:73], v[18:21]
	v_mfma_f32_16x16x32_bf16 v[18:21], v[74:77], v[78:81], v[18:21]
	v_mfma_f32_16x16x32_bf16 v[18:21], v[82:85], v[86:89], v[18:21]
	s_nop 7
	ds_write_b128 v9, v[18:21]
	s_waitcnt lgkmcnt(0)
	s_barrier
	s_cbranch_vccnz .LBB0_763
	s_and_b32 s8, s15, 0x3ffffffc
	v_or_b32_e32 v2, s8, v8
	v_lshlrev_b32_e32 v38, 2, v2
	v_lshlrev_b32_e32 v2, 12, v16
	v_lshl_add_u64 v[18:19], s[82:83], 0, v[2:3]
	v_ashrrev_i32_e32 v39, 31, v38
	v_lshl_add_u64 v[18:19], v[38:39], 2, v[18:19]
	global_load_dwordx4 v[18:21], v[18:19], off
	ds_read_b128 v[22:25], v10
	ds_read_b128 v[26:29], v10 offset:2048
	ds_read_b128 v[30:33], v10 offset:4096
	ds_read_b128 v[34:37], v10 offset:6144
	v_cmp_lt_i32_e32 vcc, v13, v14
	v_lshlrev_b32_e32 v2, 10, v16
	s_waitcnt lgkmcnt(2)
	v_pk_add_f32 v[24:25], v[24:25], v[28:29]
	v_pk_add_f32 v[22:23], v[22:23], v[26:27]
	s_waitcnt lgkmcnt(0)
	v_pk_add_f32 v[26:27], v[32:33], v[36:37]
	v_pk_add_f32 v[28:29], v[30:31], v[34:35]
	v_pk_add_f32 v[24:25], v[24:25], v[26:27]
	v_pk_add_f32 v[22:23], v[22:23], v[28:29]
	v_cndmask_b32_e32 v17, v12, v13, vcc
	v_lshlrev_b32_e32 v17, 2, v17
	v_cmp_lt_i32_e32 vcc, v15, v14
	v_lshlrev_b32_e32 v2, 1, v2
	s_waitcnt vmcnt(0)
	v_pk_add_f32 v[20:21], v[20:21], v[24:25]
	v_pk_add_f32 v[18:19], v[18:19], v[22:23]
	v_mul_f32_e32 v23, v21, v21
	v_mul_f32_e32 v22, v19, v19
	v_fmac_f32_e32 v22, v18, v18
	v_fmac_f32_e32 v23, v20, v20
	v_add_f32_e32 v24, v22, v23
	ds_bpermute_b32 v17, v17, v24
	v_cndmask_b32_e32 v40, v12, v15, vcc
	v_lshlrev_b32_e32 v40, 2, v40
	v_lshl_add_u64 v[22:23], s[96:97], 0, v[2:3]
	v_lshl_add_u64 v[22:23], v[38:39], 1, v[22:23]
	s_waitcnt lgkmcnt(0)
	v_add_f32_e32 v2, v24, v17
	ds_bpermute_b32 v17, v40, v2
	v_cvt_pk_bf16_f32 v18, v18, v19
	v_cvt_pk_bf16_f32 v19, v20, v21
	v_add_co_u32_e32 v20, vcc, s14, v22
	s_nop 1
	v_addc_co_u32_e32 v21, vcc, 0, v23, vcc
	global_store_dwordx2 v[20:21], v[18:19], off
	s_and_saveexec_b64 s[8:9], s[0:1]
	s_cbranch_execz .LBB0_762
	v_lshlrev_b32_e32 v16, 2, v16
	s_waitcnt lgkmcnt(0)
	v_add_f32_e32 v2, v2, v17
	global_atomic_add_f32 v16, v2, s[6:7]
	s_branch .LBB0_762

.LBB0_956:
	v_and_or_b32 v12, s2, -16, v195
	v_mad_i64_i32 v[68:69], s[8:9], v12, s6, v[4:5]
	global_load_dwordx4 v[12:15], v[68:69], off
	s_and_b32 s7, s4, 0x60
	v_or_b32_e32 v11, s7, v9
	v_mul_u32_u24_e32 v0, 0xb00, v11
	v_lshlrev_b32_e32 v0, 1, v0
	v_lshl_add_u64 v[70:71], v[2:3], 0, v[0:1]
	global_load_dwordx4 v[16:19], v[68:69], off offset:64
	global_load_dwordx4 v[20:23], v[70:71], off
	global_load_dwordx4 v[24:27], v[70:71], off offset:64
	global_load_dwordx4 v[28:31], v[68:69], off offset:128
	global_load_dwordx4 v[32:35], v[68:69], off offset:192
	global_load_dwordx4 v[36:39], v[70:71], off offset:128
	global_load_dwordx4 v[40:43], v[70:71], off offset:192
	global_load_dwordx4 v[44:47], v[68:69], off offset:256
	global_load_dwordx4 v[48:51], v[68:69], off offset:320
	global_load_dwordx4 v[52:55], v[70:71], off offset:256
	global_load_dwordx4 v[56:59], v[70:71], off offset:320
	global_load_dwordx4 v[60:63], v[68:69], off offset:384
	global_load_dwordx4 v[64:67], v[68:69], off offset:448
	s_and_b64 vcc, exec, s[0:1]
	global_load_dwordx4 v[72:75], v[70:71], off offset:384
	global_load_dwordx4 v[76:79], v[70:71], off offset:448
	global_load_dwordx4 v[80:83], v[68:69], off offset:512
	global_load_dwordx4 v[84:87], v[68:69], off offset:576
	global_load_dwordx4 v[88:91], v[70:71], off offset:512
	global_load_dwordx4 v[92:95], v[70:71], off offset:576
	global_load_dwordx4 v[96:99], v[68:69], off offset:640
	global_load_dwordx4 v[100:103], v[68:69], off offset:704
	global_load_dwordx4 v[104:107], v[70:71], off offset:640
	global_load_dwordx4 v[108:111], v[68:69], off offset:768
	global_load_dwordx4 v[112:115], v[70:71], off offset:704
	global_load_dwordx4 v[116:119], v[70:71], off offset:768
	global_load_dwordx4 v[120:123], v[68:69], off offset:832
	global_load_dwordx4 v[124:127], v[70:71], off offset:832
	global_load_dwordx4 v[128:131], v[68:69], off offset:896
	global_load_dwordx4 v[132:135], v[68:69], off offset:960
	global_load_dwordx4 v[136:139], v[70:71], off offset:896
	global_load_dwordx4 v[140:143], v[68:69], off offset:1024
	global_load_dwordx4 v[144:147], v[70:71], off offset:960
	global_load_dwordx4 v[148:151], v[70:71], off offset:1024
	global_load_dwordx4 v[152:155], v[68:69], off offset:1088
	global_load_dwordx4 v[156:159], v[70:71], off offset:1088
	global_load_dwordx4 v[160:163], v[68:69], off offset:1152
	global_load_dwordx4 v[164:167], v[68:69], off offset:1216
	global_load_dwordx4 v[168:171], v[70:71], off offset:1152
	global_load_dwordx4 v[172:175], v[70:71], off offset:1216
	global_load_dwordx4 v[176:179], v[68:69], off offset:1280
	global_load_dwordx4 v[180:183], v[68:69], off offset:1344
	global_load_dwordx4 v[184:187], v[70:71], off offset:1280
	global_load_dwordx4 v[188:191], v[70:71], off offset:1344
	s_waitcnt vmcnt(0)
	v_mfma_f32_16x16x32_bf16 v[12:15], v[12:15], v[20:23], 0
	v_mfma_f32_16x16x32_bf16 v[12:15], v[16:19], v[24:27], v[12:15]
	v_mfma_f32_16x16x32_bf16 v[12:15], v[28:31], v[36:39], v[12:15]
	v_mfma_f32_16x16x32_bf16 v[12:15], v[32:35], v[40:43], v[12:15]
	v_mfma_f32_16x16x32_bf16 v[12:15], v[44:47], v[52:55], v[12:15]
	v_mfma_f32_16x16x32_bf16 v[12:15], v[48:51], v[56:59], v[12:15]
	v_mfma_f32_16x16x32_bf16 v[12:15], v[60:63], v[72:75], v[12:15]
	v_mfma_f32_16x16x32_bf16 v[12:15], v[64:67], v[76:79], v[12:15]
	v_mfma_f32_16x16x32_bf16 v[12:15], v[80:83], v[88:91], v[12:15]
	v_mfma_f32_16x16x32_bf16 v[12:15], v[84:87], v[92:95], v[12:15]
	v_mfma_f32_16x16x32_bf16 v[12:15], v[96:99], v[104:107], v[12:15]
	v_mfma_f32_16x16x32_bf16 v[12:15], v[100:103], v[112:115], v[12:15]
	v_mfma_f32_16x16x32_bf16 v[12:15], v[108:111], v[116:119], v[12:15]
	v_mfma_f32_16x16x32_bf16 v[12:15], v[120:123], v[124:127], v[12:15]
	v_mfma_f32_16x16x32_bf16 v[12:15], v[128:131], v[136:139], v[12:15]
	v_mfma_f32_16x16x32_bf16 v[12:15], v[132:135], v[144:147], v[12:15]
	v_mfma_f32_16x16x32_bf16 v[12:15], v[140:143], v[148:151], v[12:15]
	v_mfma_f32_16x16x32_bf16 v[12:15], v[152:155], v[156:159], v[12:15]
	v_mfma_f32_16x16x32_bf16 v[12:15], v[160:163], v[168:171], v[12:15]
	v_mfma_f32_16x16x32_bf16 v[12:15], v[164:167], v[172:175], v[12:15]
	v_mfma_f32_16x16x32_bf16 v[12:15], v[176:179], v[184:187], v[12:15]
	v_mfma_f32_16x16x32_bf16 v[12:15], v[180:183], v[188:191], v[12:15]
	s_nop 7
	ds_write_b128 v7, v[12:15]
	s_waitcnt lgkmcnt(0)
	s_barrier
	s_cbranch_vccnz .LBB0_955
	s_and_b32 s7, s63, 0x3ffffffc
	v_or_b32_e32 v0, s7, v6
	v_lshl_or_b32 v11, v11, 10, v10
	v_lshlrev_b32_e32 v28, 2, v0
	v_lshlrev_b32_e32 v0, 1, v11
	v_lshl_add_u64 v[12:13], s[96:97], 0, v[0:1]
	v_ashrrev_i32_e32 v29, 31, v28
	v_lshl_add_u64 v[12:13], v[28:29], 1, v[12:13]
	global_load_dwordx2 v[30:31], v[12:13], off
	ds_read_b128 v[12:15], v8
	ds_read_b128 v[16:19], v8 offset:2048
	ds_read_b128 v[20:23], v8 offset:4096
	ds_read_b128 v[24:27], v8 offset:6144
	v_lshlrev_b32_e32 v0, 2, v11
	v_lshl_add_u64 v[32:33], s[70:71], 0, v[0:1]
	s_waitcnt lgkmcnt(2)
	v_pk_add_f32 v[14:15], v[14:15], v[18:19]
	v_pk_add_f32 v[12:13], v[12:13], v[16:17]
	s_waitcnt lgkmcnt(0)
	v_pk_add_f32 v[16:17], v[22:23], v[26:27]
	v_pk_add_f32 v[18:19], v[20:21], v[24:25]
	v_pk_add_f32 v[14:15], v[14:15], v[16:17]
	v_pk_add_f32 v[12:13], v[12:13], v[18:19]
	s_waitcnt vmcnt(0)
	v_lshlrev_b32_e32 v16, 16, v30
	v_and_b32_e32 v17, 0xffff0000, v30
	v_lshlrev_b32_e32 v18, 16, v31
	v_and_b32_e32 v19, 0xffff0000, v31
	v_pk_add_f32 v[14:15], v[14:15], v[18:19]
	v_pk_add_f32 v[12:13], v[12:13], v[16:17]
	v_lshl_add_u64 v[16:17], v[28:29], 2, v[32:33]
	global_store_dwordx4 v[16:17], v[12:15], off
	s_branch .LBB0_955
